# compress MLP weights W1^T written by the prep phase in MFMA-fragment-major order so every K-loop load instruction reads 1 KB contiguous (SGPR base + lane offset, no per-load address VALU)
# speedup vs baseline: 1.0040x; 1.0040x over previous
; DI unsigned pk2(float a, float b) { f32x2_t v = {a, b}; return __builtin_bit_cast(unsigned, __builtin_convertvector(v, bf16x2_t)); }
; DI void tconv(const float* __restrict__ src, int K, int N, int Npad, bf16_t* __restrict__ dst, int mode, float* tile, const float* __restrict__ gk = nullptr) {
;     ...
;         { const int nl = tid >> 2, kg = tid & 3, n = tn * 128 + nl;
;           float x[16];
; #pragma unroll
;           for (int j = 0; j < 16; ++j) x[j] = tile[(kg * 16 + j) * 129 + nl];
;           const int drow = mode == 0 ? n : (tn * 256 + nl + (mode == 2 ? 128 : 0));
;           u32x4 w0, w1; w0.x = pk2(x[0], x[1]); w0.y = pk2(x[2], x[3]); w0.z = pk2(x[4], x[5]); w0.w = pk2(x[6], x[7]);
;           w1.x = pk2(x[8], x[9]); w1.y = pk2(x[10], x[11]); w1.z = pk2(x[12], x[13]); w1.w = pk2(x[14], x[15]);
;           u32x4* dp = (u32x4*)(dst + (size_t)drow * K + tk * 64 + kg * 16); dp[0] = w0; dp[1] = w1; }
.LBB0_89:
	v_add_u32_e32 v67, 0x400, v55
	ds_read2_b32 v[70:71], v67 offset0:2 offset1:131
	v_add_u32_e32 v67, 0x800, v55
	ds_read2_b32 v[72:73], v67 offset0:4 offset1:133
	v_add_u32_e32 v67, 0xc00, v55
	s_ashr_i32 s20, s18, 31
	ds_read2_b32 v[74:75], v67 offset0:6 offset1:135
	v_add_u32_e32 v67, 0x1000, v55
	s_lshr_b32 s20, s20, 26
	ds_read2_b32 v[68:69], v55 offset1:129
	ds_read2_b32 v[76:77], v67 offset0:8 offset1:137
	s_add_i32 s18, s18, s20
	v_add_u32_e32 v67, 0x1400, v55
	s_ashr_i32 s18, s18, 6
	ds_read2_b32 v[78:79], v67 offset0:10 offset1:139
	v_add_u32_e32 v67, 0x1800, v55
	ds_read2_b32 v[80:81], v67 offset0:12 offset1:141
	v_add_u32_e32 v67, 0x1c00, v55
	v_lshl_add_u32 v84, s18, 7, v53
	ds_read2_b32 v[82:83], v67 offset0:14 offset1:143
	s_lshl_b32 s18, s18, 12
	s_waitcnt lgkmcnt(4)
	v_cvt_pk_bf16_f32 v68, v68, v69
	v_cvt_pk_bf16_f32 v69, v70, v71
	v_cvt_pk_bf16_f32 v70, v72, v73
	s_waitcnt lgkmcnt(3)
	v_cvt_pk_bf16_f32 v72, v76, v77
	s_sub_i32 s20, s17, s18
	s_ashr_i32 s21, s20, 31
	v_cvt_pk_bf16_f32 v71, v74, v75
	v_lshrrev_b32_e32 v85, 4, v84
	v_and_b32_e32 v76, 15, v84
	v_lshlrev_b32_e32 v76, 4, v76
	v_lshl_or_b32 v76, v85, 10, v76
	v_lshrrev_b32_e32 v85, 5, v18
	v_and_b32_e32 v77, 1, v85
	v_lshl_or_b32 v76, v77, 9, v76
	v_lshrrev_b32_e32 v85, 1, v85
	v_lshl_or_b32 v76, v85, 13, v76
	s_lshl_b32 s20, s20, 8
	v_add_u32_e32 v76, s20, v76
	v_mov_b32_e32 v77, 0
	v_lshl_add_u64 v[76:77], s[6:7], 0, v[76:77]
	s_add_i32 s17, s17, s15
	s_andn2_b64 vcc, exec, s[8:9]
	s_mov_b32 s18, s19
	s_waitcnt lgkmcnt(2)
	v_cvt_pk_bf16_f32 v73, v78, v79
	s_waitcnt lgkmcnt(1)
	v_cvt_pk_bf16_f32 v74, v80, v81
	s_waitcnt lgkmcnt(0)
	v_cvt_pk_bf16_f32 v75, v82, v83
	global_store_dwordx4 v[76:77], v[68:71], off
	global_store_dwordx4 v[76:77], v[72:75], off offset:256
	s_barrier
	s_cbranch_vccz .LBB0_92

; DI unsigned pk2(float a, float b) { f32x2_t v = {a, b}; return __builtin_bit_cast(unsigned, __builtin_convertvector(v, bf16x2_t)); }
; DI void tconv(const float* __restrict__ src, int K, int N, int Npad, bf16_t* __restrict__ dst, int mode, float* tile, const float* __restrict__ gk = nullptr) {
;     ...
;         { const int nl = tid >> 2, kg = tid & 3, n = tn * 128 + nl;
;           float x[16];
; #pragma unroll
;           for (int j = 0; j < 16; ++j) x[j] = tile[(kg * 16 + j) * 129 + nl];
;           const int drow = mode == 0 ? n : (tn * 256 + nl + (mode == 2 ? 128 : 0));
;           u32x4 w0, w1; w0.x = pk2(x[0], x[1]); w0.y = pk2(x[2], x[3]); w0.z = pk2(x[4], x[5]); w0.w = pk2(x[6], x[7]);
;           w1.x = pk2(x[8], x[9]); w1.y = pk2(x[10], x[11]); w1.z = pk2(x[12], x[13]); w1.w = pk2(x[14], x[15]);
;           u32x4* dp = (u32x4*)(dst + (size_t)drow * K + tk * 64 + kg * 16); dp[0] = w0; dp[1] = w1; }
.LBB0_93:
	v_add_u32_e32 v43, 0x400, v55
	ds_read2_b32 v[46:47], v43 offset0:2 offset1:131
	v_add_u32_e32 v43, 0x800, v55
	ds_read2_b32 v[48:49], v43 offset0:4 offset1:133
	v_add_u32_e32 v43, 0xc00, v55
	s_ashr_i32 s19, s17, 31
	ds_read2_b32 v[50:51], v43 offset0:6 offset1:135
	v_add_u32_e32 v43, 0x1000, v55
	s_lshr_b32 s19, s19, 26
	ds_read2_b32 v[44:45], v55 offset1:129
	ds_read2_b32 v[66:67], v43 offset0:8 offset1:137
	s_add_i32 s17, s17, s19
	v_add_u32_e32 v43, 0x1400, v55
	s_ashr_i32 s17, s17, 6
	ds_read2_b32 v[68:69], v43 offset0:10 offset1:139
	v_add_u32_e32 v43, 0x1800, v55
	ds_read2_b32 v[70:71], v43 offset0:12 offset1:141
	v_add_u32_e32 v43, 0x1c00, v55
	v_lshl_add_u32 v74, s17, 7, v53
	ds_read2_b32 v[72:73], v43 offset0:14 offset1:143
	s_lshl_b32 s17, s17, 12
	s_waitcnt lgkmcnt(4)
	v_cvt_pk_bf16_f32 v44, v44, v45
	v_cvt_pk_bf16_f32 v45, v46, v47
	v_cvt_pk_bf16_f32 v46, v48, v49
	s_waitcnt lgkmcnt(3)
	v_cvt_pk_bf16_f32 v48, v66, v67
	s_sub_i32 s20, s14, s17
	s_ashr_i32 s21, s20, 31
	v_cvt_pk_bf16_f32 v47, v50, v51
	v_lshrrev_b32_e32 v75, 4, v74
	v_and_b32_e32 v66, 15, v74
	v_lshlrev_b32_e32 v66, 4, v66
	v_lshl_or_b32 v66, v75, 10, v66
	v_lshrrev_b32_e32 v75, 5, v18
	v_and_b32_e32 v67, 1, v75
	v_lshl_or_b32 v66, v67, 9, v66
	v_lshrrev_b32_e32 v75, 1, v75
	v_lshl_or_b32 v66, v75, 13, v66
	s_lshl_b32 s20, s20, 8
	v_add_u32_e32 v66, s20, v66
	v_mov_b32_e32 v67, 0
	v_lshl_add_u64 v[66:67], s[6:7], 0, v[66:67]
	s_add_i32 s14, s14, s15
	s_and_b64 vcc, exec, s[8:9]
	s_mov_b32 s17, s18
	s_waitcnt lgkmcnt(2)
	v_cvt_pk_bf16_f32 v49, v68, v69
	s_waitcnt lgkmcnt(1)
	v_cvt_pk_bf16_f32 v50, v70, v71
	s_waitcnt lgkmcnt(0)
	v_cvt_pk_bf16_f32 v51, v72, v73
	global_store_dwordx4 v[66:67], v[44:47], off
	global_store_dwordx4 v[66:67], v[48:51], off offset:256
	s_barrier
	s_cbranch_vccnz .LBB0_96

; #define CP_LOAD(buf, s_) do { const int kabs_ = 512 * wid + 32 * (s_) + 8 * q; fa[buf] = *(const bf16x8*)(arow + (size_t)(kabs_ >> 7) * NPROJ + (kabs_ & 127)); \
;         _Pragma("unroll") for (int ct = 0; ct < 8; ++ct) fb[buf][ct] = *(const bf16x8*)(w1t + (size_t)(ct * 16 + r) * 4096 + kabs_); } while (0)
; DI void compress_item(const Params& P, int item, unsigned char* smem) {
;     ...
;     const int grow = rt * 16 + r, bg = grow / 127, c = grow % 127, b = bg >> 1, g = bg & 1;
;     const bf16_t* arow = proj + (size_t)(b * TT + 16 * c) * NPROJ + (which ? C_VC : C_KC) + g * 128;
;     f32x4 acc[8];
; #pragma unroll
;     for (int ct = 0; ct < 8; ++ct) acc[ct] = (f32x4){0.f, 0.f, 0.f, 0.f};
;     bf16x8 fa[2], fb[2][8];
;     ...
;     CP_LOAD(0, 0);
; #pragma unroll
;     for (int s = 0; s < 16; ++s) {
;         if (s + 1 < 16) CP_LOAD((s + 1) & 1, s + 1);
.LBB0_637:
	s_andn2_b64 vcc, exec, s[4:5]
	s_cbranch_vccnz .LBB0_634
	s_mul_hi_i32 s4, s71, 0x81020409
	s_add_i32 s4, s4, s71
	s_lshr_b32 s5, s4, 31
	s_ashr_i32 s4, s4, 6
	s_add_i32 s72, s4, s5
	s_mul_i32 s73, s72, 0xfffff810
	v_add_u32_e32 v2, s33, v1
	v_add_u32_e32 v3, s73, v2
	v_mul_hi_i32 v4, v3, s59
	v_add_u32_e32 v3, v4, v3
	s_add_i32 s14, s71, 0x7e
	v_lshrrev_b32_e32 v4, 31, v3
	v_ashrrev_i32_e32 v3, 6, v3
	s_cmpk_gt_u32 s14, 0xfc
	v_add_u32_e32 v4, v3, v4
	s_cselect_b64 s[46:47], -1, 0
	s_lshl_b32 s4, s72, 7
	v_mul_lo_u32 v3, v4, s68
	s_mulk_i32 s72, 0x7f0
	v_subrev_u32_e32 v3, s72, v3
	s_ashr_i32 s5, s4, 31
	v_add_u32_e32 v2, v2, v3
	v_lshlrev_b32_e32 v3, 10, v4
	s_cmpk_lt_u32 s14, 0xfd
	v_and_b32_e32 v3, 0xfffff800, v3
	v_readlane_b32 s80, v245, 5
	s_cselect_b32 s76, s60, 0x9e00000
	v_lshl_add_u32 v5, v2, 4, v3
	v_readlane_b32 s82, v245, 7
	v_mov_b64_e32 v[2:3], s[12:13]
	s_cselect_b32 s14, s61, 0x9f08000
	s_cselect_b32 s74, s69, 0xa00
	s_mov_b32 s75, s15
	v_readlane_b32 s83, v245, 8
	s_add_u32 s76, s82, s76
	v_mad_i64_i32 v[2:3], s[78:79], v5, s53, v[2:3]
	v_lshlrev_b32_e32 v4, 8, v4
	s_addc_u32 s77, s83, 0
	v_lshl_add_u64 v[2:3], v[2:3], 0, s[74:75]
	v_and_b32_e32 v46, 0x100, v4
	v_mov_b32_e32 v59, v47
	v_lshl_add_u64 v[6:7], v[2:3], 0, v[46:47]
	v_mov_b32_e32 v55, v47
	v_lshl_add_u64 v[2:3], s[76:77], 0, v[58:59]
	v_lshl_add_u64 v[44:45], v[6:7], 0, v[54:55]
	v_mov_b32_e32 v57, v47
	v_mov_b32_e32 v63, v47
	v_mov_b32_e32 v65, v47
	v_mov_b32_e32 v67, v47
	v_mov_b32_e32 v69, v47
	v_mov_b32_e32 v71, v47
	v_mov_b32_e32 v73, v47
	v_mov_b32_e32 v75, v47
	v_mov_b32_e32 v77, v47
	v_lshl_add_u64 v[124:125], v[2:3], 0, 64
	v_lshl_add_u64 v[8:9], v[44:45], 0, v[56:57]
	v_mov_b32_e32 v61, v47
	v_lshl_add_u64 v[40:41], v[2:3], 0, v[62:63]
	v_lshl_add_u64 v[16:17], v[2:3], 0, v[64:65]
	v_lshl_add_u64 v[20:21], v[2:3], 0, v[66:67]
	v_lshl_add_u64 v[24:25], v[2:3], 0, v[68:69]
	v_lshl_add_u64 v[28:29], v[2:3], 0, v[70:71]
	v_lshl_add_u64 v[32:33], v[2:3], 0, v[72:73]
	v_lshl_add_u64 v[36:37], v[2:3], 0, v[74:75]
	v_lshl_add_u64 v[88:89], v[44:45], 0, v[76:77]
	v_lshl_add_u64 v[104:105], v[124:125], 0, v[62:63]
	v_lshl_add_u64 v[4:5], v[2:3], 0, v[60:61]
	v_readlane_b32 s81, v245, 6
	v_readlane_b32 s84, v245, 9
	v_readlane_b32 s85, v245, 10
	v_readlane_b32 s86, v245, 11
	v_readlane_b32 s87, v245, 12
	v_mov_b32_e32 v79, v47
	v_mov_b32_e32 v81, v47
	v_mov_b32_e32 v83, v47
	v_mov_b32_e32 v85, v47
	v_mov_b32_e32 v87, v47
	v_lshl_add_u64 v[34:35], v[6:7], 0, v[56:57]
	v_lshrrev_b32_e32 v37, 6, v206
	v_and_b32_e32 v36, 63, v206
	v_readfirstlane_b32 s89, v37
	v_lshlrev_b32_e32 v36, 4, v36
	s_lshl_b32 s89, s89, 17
	s_add_u32 s90, s76, s89
	s_addc_u32 s91, s77, 0
	s_add_u32 s92, s90, 0x1000
	s_addc_u32 s93, s91, 0
	v_lshl_add_u64 v[96:97], v[34:35], 0, v[54:55]
	global_load_dwordx4 v[96:99], v[96:97], off
	global_load_dwordx4 v[100:103], v36, s[90:91]
	global_load_dwordx4 v[104:107], v36, s[90:91] offset:1024
	global_load_dwordx4 v[108:111], v36, s[90:91] offset:2048
	global_load_dwordx4 v[112:115], v36, s[90:91] offset:3072
	global_load_dwordx4 v[116:119], v36, s[92:93]
	global_load_dwordx4 v[120:123], v36, s[92:93] offset:1024
	global_load_dwordx4 v[124:127], v36, s[92:93] offset:2048
	global_load_dwordx4 v[128:131], v36, s[92:93] offset:3072
	s_add_u32 s90, s90, 0x2000
	s_addc_u32 s91, s91, 0
	s_add_u32 s92, s92, 0x2000
	s_addc_u32 s93, s93, 0
	v_lshl_add_u64 v[132:133], v[34:35], 0, v[54:55]
	global_load_dwordx4 v[132:135], v[132:133], off offset:64
	global_load_dwordx4 v[136:139], v36, s[90:91]
	global_load_dwordx4 v[140:143], v36, s[90:91] offset:1024
	global_load_dwordx4 v[144:147], v36, s[90:91] offset:2048
	global_load_dwordx4 v[148:151], v36, s[90:91] offset:3072
	global_load_dwordx4 v[152:155], v36, s[92:93]
	global_load_dwordx4 v[156:159], v36, s[92:93] offset:1024
	global_load_dwordx4 v[160:163], v36, s[92:93] offset:2048
	global_load_dwordx4 v[164:167], v36, s[92:93] offset:3072
	s_add_u32 s90, s90, 0x2000
	s_addc_u32 s91, s91, 0
	s_add_u32 s92, s92, 0x2000
	s_addc_u32 s93, s93, 0
	v_lshl_add_u64 v[168:169], v[34:35], 0, v[54:55]
	global_load_dwordx4 v[168:171], v[168:169], off offset:128
	global_load_dwordx4 v[172:175], v36, s[90:91]
	global_load_dwordx4 v[176:179], v36, s[90:91] offset:1024
	global_load_dwordx4 v[180:183], v36, s[90:91] offset:2048
	global_load_dwordx4 v[184:187], v36, s[90:91] offset:3072
	global_load_dwordx4 v[188:191], v36, s[92:93]
	global_load_dwordx4 v[192:195], v36, s[92:93] offset:1024
	global_load_dwordx4 v[196:199], v36, s[92:93] offset:2048
	global_load_dwordx4 v[200:203], v36, s[92:93] offset:3072
	s_add_u32 s90, s90, 0x2000
	s_addc_u32 s91, s91, 0
	s_add_u32 s92, s92, 0x2000
	s_addc_u32 s93, s93, 0
	v_lshl_add_u64 v[208:209], v[34:35], 0, v[54:55]
	global_load_dwordx4 v[208:211], v[208:209], off offset:192
	global_load_dwordx4 v[212:215], v36, s[90:91]
	global_load_dwordx4 v[216:219], v36, s[90:91] offset:1024
	global_load_dwordx4 v[220:223], v36, s[90:91] offset:2048
	global_load_dwordx4 v[224:227], v36, s[90:91] offset:3072
	global_load_dwordx4 v[228:231], v36, s[92:93]
	global_load_dwordx4 v[232:235], v36, s[92:93] offset:1024
	global_load_dwordx4 v[236:239], v36, s[92:93] offset:2048
	global_load_dwordx4 v[240:243], v36, s[92:93] offset:3072
	s_add_u32 s90, s90, 0x2000
	s_addc_u32 s91, s91, 0
	s_add_u32 s92, s92, 0x2000
	s_addc_u32 s93, s93, 0
	s_waitcnt vmcnt(27)
; #define CP_LOAD(buf, s_) do { const int kabs_ = 512 * wid + 32 * (s_) + 8 * q; fa[buf] = *(const bf16x8*)(arow + (size_t)(kabs_ >> 7) * NPROJ + (kabs_ & 127)); \
;         _Pragma("unroll") for (int ct = 0; ct < 8; ++ct) fb[buf][ct] = *(const bf16x8*)(w1t + (size_t)(ct * 16 + r) * 4096 + kabs_); } while (0)
; DI void compress_item(const Params& P, int item, unsigned char* smem) {
;     ...
; #pragma unroll
;     for (int s = 0; s < 16; ++s) {
;         if (s + 1 < 16) CP_LOAD((s + 1) & 1, s + 1);
;         __builtin_amdgcn_sched_barrier(0);
; #pragma unroll
;         for (int ct = 0; ct < 8; ++ct) acc[ct] = __builtin_amdgcn_mfma_f32_16x16x32_bf16(fa[s & 1], fb[s & 1][ct], acc[ct], 0, 0, 0);
;         __builtin_amdgcn_sched_barrier(0);
;     }
	v_mfma_f32_16x16x32_bf16 v[2:5], v[96:99], v[100:103], 0
	v_mfma_f32_16x16x32_bf16 v[10:13], v[96:99], v[104:107], 0
	v_mfma_f32_16x16x32_bf16 v[14:17], v[96:99], v[108:111], 0
	v_mfma_f32_16x16x32_bf16 v[18:21], v[96:99], v[112:115], 0
	v_mfma_f32_16x16x32_bf16 v[22:25], v[96:99], v[116:119], 0
	v_mfma_f32_16x16x32_bf16 v[26:29], v[96:99], v[120:123], 0
	v_mfma_f32_16x16x32_bf16 v[30:33], v[96:99], v[124:127], 0
	v_mfma_f32_16x16x32_bf16 v[6:9], v[96:99], v[128:131], 0
	v_lshl_add_u64 v[96:97], v[34:35], 0, v[82:83]
	global_load_dwordx4 v[96:99], v[96:97], off
	global_load_dwordx4 v[100:103], v36, s[90:91]
	global_load_dwordx4 v[104:107], v36, s[90:91] offset:1024
	global_load_dwordx4 v[108:111], v36, s[90:91] offset:2048
	global_load_dwordx4 v[112:115], v36, s[90:91] offset:3072
	global_load_dwordx4 v[116:119], v36, s[92:93]
	global_load_dwordx4 v[120:123], v36, s[92:93] offset:1024
	global_load_dwordx4 v[124:127], v36, s[92:93] offset:2048
	global_load_dwordx4 v[128:131], v36, s[92:93] offset:3072
	s_add_u32 s90, s90, 0x2000
	s_addc_u32 s91, s91, 0
	s_add_u32 s92, s92, 0x2000
	s_addc_u32 s93, s93, 0
	s_waitcnt vmcnt(27)
	v_mfma_f32_16x16x32_bf16 v[2:5], v[132:135], v[136:139], v[2:5]
	v_mfma_f32_16x16x32_bf16 v[10:13], v[132:135], v[140:143], v[10:13]
	v_mfma_f32_16x16x32_bf16 v[14:17], v[132:135], v[144:147], v[14:17]
	v_mfma_f32_16x16x32_bf16 v[18:21], v[132:135], v[148:151], v[18:21]
	v_mfma_f32_16x16x32_bf16 v[22:25], v[132:135], v[152:155], v[22:25]
	v_mfma_f32_16x16x32_bf16 v[26:29], v[132:135], v[156:159], v[26:29]
	v_mfma_f32_16x16x32_bf16 v[30:33], v[132:135], v[160:163], v[30:33]
	v_mfma_f32_16x16x32_bf16 v[6:9], v[132:135], v[164:167], v[6:9]
	v_lshl_add_u64 v[132:133], v[34:35], 0, v[82:83]
	global_load_dwordx4 v[132:135], v[132:133], off offset:64
	global_load_dwordx4 v[136:139], v36, s[90:91]
	global_load_dwordx4 v[140:143], v36, s[90:91] offset:1024
	global_load_dwordx4 v[144:147], v36, s[90:91] offset:2048
	global_load_dwordx4 v[148:151], v36, s[90:91] offset:3072
	global_load_dwordx4 v[152:155], v36, s[92:93]
	global_load_dwordx4 v[156:159], v36, s[92:93] offset:1024
	global_load_dwordx4 v[160:163], v36, s[92:93] offset:2048
	global_load_dwordx4 v[164:167], v36, s[92:93] offset:3072
	s_add_u32 s90, s90, 0x2000
	s_addc_u32 s91, s91, 0
	s_add_u32 s92, s92, 0x2000
	s_addc_u32 s93, s93, 0
	s_waitcnt vmcnt(27)
	v_mfma_f32_16x16x32_bf16 v[2:5], v[168:171], v[172:175], v[2:5]
	v_mfma_f32_16x16x32_bf16 v[10:13], v[168:171], v[176:179], v[10:13]
	v_mfma_f32_16x16x32_bf16 v[14:17], v[168:171], v[180:183], v[14:17]
	v_mfma_f32_16x16x32_bf16 v[18:21], v[168:171], v[184:187], v[18:21]
	v_mfma_f32_16x16x32_bf16 v[22:25], v[168:171], v[188:191], v[22:25]
	v_mfma_f32_16x16x32_bf16 v[26:29], v[168:171], v[192:195], v[26:29]
	v_mfma_f32_16x16x32_bf16 v[30:33], v[168:171], v[196:199], v[30:33]
	v_mfma_f32_16x16x32_bf16 v[6:9], v[168:171], v[200:203], v[6:9]
	v_lshl_add_u64 v[168:169], v[34:35], 0, v[82:83]
	global_load_dwordx4 v[168:171], v[168:169], off offset:128
	global_load_dwordx4 v[172:175], v36, s[90:91]
	global_load_dwordx4 v[176:179], v36, s[90:91] offset:1024
	global_load_dwordx4 v[180:183], v36, s[90:91] offset:2048
	global_load_dwordx4 v[184:187], v36, s[90:91] offset:3072
	global_load_dwordx4 v[188:191], v36, s[92:93]
	global_load_dwordx4 v[192:195], v36, s[92:93] offset:1024
	global_load_dwordx4 v[196:199], v36, s[92:93] offset:2048
	global_load_dwordx4 v[200:203], v36, s[92:93] offset:3072
	s_add_u32 s90, s90, 0x2000
	s_addc_u32 s91, s91, 0
	s_add_u32 s92, s92, 0x2000
	s_addc_u32 s93, s93, 0
	s_waitcnt vmcnt(27)
	v_mfma_f32_16x16x32_bf16 v[2:5], v[208:211], v[212:215], v[2:5]
	v_mfma_f32_16x16x32_bf16 v[10:13], v[208:211], v[216:219], v[10:13]
	v_mfma_f32_16x16x32_bf16 v[14:17], v[208:211], v[220:223], v[14:17]
	v_mfma_f32_16x16x32_bf16 v[18:21], v[208:211], v[224:227], v[18:21]
	v_mfma_f32_16x16x32_bf16 v[22:25], v[208:211], v[228:231], v[22:25]
	v_mfma_f32_16x16x32_bf16 v[26:29], v[208:211], v[232:235], v[26:29]
	v_mfma_f32_16x16x32_bf16 v[30:33], v[208:211], v[236:239], v[30:33]
	v_mfma_f32_16x16x32_bf16 v[6:9], v[208:211], v[240:243], v[6:9]
	v_lshl_add_u64 v[208:209], v[34:35], 0, v[82:83]
	global_load_dwordx4 v[208:211], v[208:209], off offset:192
	global_load_dwordx4 v[212:215], v36, s[90:91]
	global_load_dwordx4 v[216:219], v36, s[90:91] offset:1024
	global_load_dwordx4 v[220:223], v36, s[90:91] offset:2048
	global_load_dwordx4 v[224:227], v36, s[90:91] offset:3072
	global_load_dwordx4 v[228:231], v36, s[92:93]
	global_load_dwordx4 v[232:235], v36, s[92:93] offset:1024
	global_load_dwordx4 v[236:239], v36, s[92:93] offset:2048
	global_load_dwordx4 v[240:243], v36, s[92:93] offset:3072
	s_add_u32 s90, s90, 0x2000
	s_addc_u32 s91, s91, 0
	s_add_u32 s92, s92, 0x2000
	s_addc_u32 s93, s93, 0
	s_waitcnt vmcnt(27)
	v_mfma_f32_16x16x32_bf16 v[2:5], v[96:99], v[100:103], v[2:5]
	v_mfma_f32_16x16x32_bf16 v[10:13], v[96:99], v[104:107], v[10:13]
	v_mfma_f32_16x16x32_bf16 v[14:17], v[96:99], v[108:111], v[14:17]
	v_mfma_f32_16x16x32_bf16 v[18:21], v[96:99], v[112:115], v[18:21]
	v_mfma_f32_16x16x32_bf16 v[22:25], v[96:99], v[116:119], v[22:25]
	v_mfma_f32_16x16x32_bf16 v[26:29], v[96:99], v[120:123], v[26:29]
	v_mfma_f32_16x16x32_bf16 v[30:33], v[96:99], v[124:127], v[30:33]
	v_mfma_f32_16x16x32_bf16 v[6:9], v[96:99], v[128:131], v[6:9]
	v_lshl_add_u64 v[96:97], v[34:35], 0, v[84:85]
	global_load_dwordx4 v[96:99], v[96:97], off
	global_load_dwordx4 v[100:103], v36, s[90:91]
	global_load_dwordx4 v[104:107], v36, s[90:91] offset:1024
	global_load_dwordx4 v[108:111], v36, s[90:91] offset:2048
	global_load_dwordx4 v[112:115], v36, s[90:91] offset:3072
	global_load_dwordx4 v[116:119], v36, s[92:93]
	global_load_dwordx4 v[120:123], v36, s[92:93] offset:1024
	global_load_dwordx4 v[124:127], v36, s[92:93] offset:2048
	global_load_dwordx4 v[128:131], v36, s[92:93] offset:3072
	s_add_u32 s90, s90, 0x2000
	s_addc_u32 s91, s91, 0
	s_add_u32 s92, s92, 0x2000
	s_addc_u32 s93, s93, 0
	s_waitcnt vmcnt(27)
; #define CP_LOAD(buf, s_) do { const int kabs_ = 512 * wid + 32 * (s_) + 8 * q; fa[buf] = *(const bf16x8*)(arow + (size_t)(kabs_ >> 7) * NPROJ + (kabs_ & 127)); \
;         _Pragma("unroll") for (int ct = 0; ct < 8; ++ct) fb[buf][ct] = *(const bf16x8*)(w1t + (size_t)(ct * 16 + r) * 4096 + kabs_); } while (0)
; DI void compress_item(const Params& P, int item, unsigned char* smem) {
;     ...
; #pragma unroll
;     for (int s = 0; s < 16; ++s) {
;         if (s + 1 < 16) CP_LOAD((s + 1) & 1, s + 1);
;         __builtin_amdgcn_sched_barrier(0);
; #pragma unroll
;         for (int ct = 0; ct < 8; ++ct) acc[ct] = __builtin_amdgcn_mfma_f32_16x16x32_bf16(fa[s & 1], fb[s & 1][ct], acc[ct], 0, 0, 0);
;         __builtin_amdgcn_sched_barrier(0);
;     }
	v_mfma_f32_16x16x32_bf16 v[2:5], v[132:135], v[136:139], v[2:5]
	v_mfma_f32_16x16x32_bf16 v[10:13], v[132:135], v[140:143], v[10:13]
	v_mfma_f32_16x16x32_bf16 v[14:17], v[132:135], v[144:147], v[14:17]
	v_mfma_f32_16x16x32_bf16 v[18:21], v[132:135], v[148:151], v[18:21]
	v_mfma_f32_16x16x32_bf16 v[22:25], v[132:135], v[152:155], v[22:25]
	v_mfma_f32_16x16x32_bf16 v[26:29], v[132:135], v[156:159], v[26:29]
	v_mfma_f32_16x16x32_bf16 v[30:33], v[132:135], v[160:163], v[30:33]
	v_mfma_f32_16x16x32_bf16 v[6:9], v[132:135], v[164:167], v[6:9]
	v_lshl_add_u64 v[132:133], v[34:35], 0, v[84:85]
	global_load_dwordx4 v[132:135], v[132:133], off offset:64
	global_load_dwordx4 v[136:139], v36, s[90:91]
	global_load_dwordx4 v[140:143], v36, s[90:91] offset:1024
	global_load_dwordx4 v[144:147], v36, s[90:91] offset:2048
	global_load_dwordx4 v[148:151], v36, s[90:91] offset:3072
	global_load_dwordx4 v[152:155], v36, s[92:93]
	global_load_dwordx4 v[156:159], v36, s[92:93] offset:1024
	global_load_dwordx4 v[160:163], v36, s[92:93] offset:2048
	global_load_dwordx4 v[164:167], v36, s[92:93] offset:3072
	s_add_u32 s90, s90, 0x2000
	s_addc_u32 s91, s91, 0
	s_add_u32 s92, s92, 0x2000
	s_addc_u32 s93, s93, 0
	s_waitcnt vmcnt(27)
	v_mfma_f32_16x16x32_bf16 v[2:5], v[168:171], v[172:175], v[2:5]
	v_mfma_f32_16x16x32_bf16 v[10:13], v[168:171], v[176:179], v[10:13]
	v_mfma_f32_16x16x32_bf16 v[14:17], v[168:171], v[180:183], v[14:17]
	v_mfma_f32_16x16x32_bf16 v[18:21], v[168:171], v[184:187], v[18:21]
	v_mfma_f32_16x16x32_bf16 v[22:25], v[168:171], v[188:191], v[22:25]
	v_mfma_f32_16x16x32_bf16 v[26:29], v[168:171], v[192:195], v[26:29]
	v_mfma_f32_16x16x32_bf16 v[30:33], v[168:171], v[196:199], v[30:33]
	v_mfma_f32_16x16x32_bf16 v[6:9], v[168:171], v[200:203], v[6:9]
	v_lshl_add_u64 v[168:169], v[34:35], 0, v[84:85]
	global_load_dwordx4 v[168:171], v[168:169], off offset:128
	global_load_dwordx4 v[172:175], v36, s[90:91]
	global_load_dwordx4 v[176:179], v36, s[90:91] offset:1024
	global_load_dwordx4 v[180:183], v36, s[90:91] offset:2048
	global_load_dwordx4 v[184:187], v36, s[90:91] offset:3072
	global_load_dwordx4 v[188:191], v36, s[92:93]
	global_load_dwordx4 v[192:195], v36, s[92:93] offset:1024
	global_load_dwordx4 v[196:199], v36, s[92:93] offset:2048
	global_load_dwordx4 v[200:203], v36, s[92:93] offset:3072
	s_add_u32 s90, s90, 0x2000
	s_addc_u32 s91, s91, 0
	s_add_u32 s92, s92, 0x2000
	s_addc_u32 s93, s93, 0
	s_waitcnt vmcnt(27)
	v_mfma_f32_16x16x32_bf16 v[2:5], v[208:211], v[212:215], v[2:5]
	v_mfma_f32_16x16x32_bf16 v[10:13], v[208:211], v[216:219], v[10:13]
	v_mfma_f32_16x16x32_bf16 v[14:17], v[208:211], v[220:223], v[14:17]
	v_mfma_f32_16x16x32_bf16 v[18:21], v[208:211], v[224:227], v[18:21]
	v_mfma_f32_16x16x32_bf16 v[22:25], v[208:211], v[228:231], v[22:25]
	v_mfma_f32_16x16x32_bf16 v[26:29], v[208:211], v[232:235], v[26:29]
	v_mfma_f32_16x16x32_bf16 v[30:33], v[208:211], v[236:239], v[30:33]
	v_mfma_f32_16x16x32_bf16 v[6:9], v[208:211], v[240:243], v[6:9]
	v_lshl_add_u64 v[208:209], v[34:35], 0, v[84:85]
	global_load_dwordx4 v[208:211], v[208:209], off offset:192
	global_load_dwordx4 v[212:215], v36, s[90:91]
	global_load_dwordx4 v[216:219], v36, s[90:91] offset:1024
	global_load_dwordx4 v[220:223], v36, s[90:91] offset:2048
	global_load_dwordx4 v[224:227], v36, s[90:91] offset:3072
	global_load_dwordx4 v[228:231], v36, s[92:93]
	global_load_dwordx4 v[232:235], v36, s[92:93] offset:1024
	global_load_dwordx4 v[236:239], v36, s[92:93] offset:2048
	global_load_dwordx4 v[240:243], v36, s[92:93] offset:3072
	s_add_u32 s90, s90, 0x2000
	s_addc_u32 s91, s91, 0
	s_add_u32 s92, s92, 0x2000
	s_addc_u32 s93, s93, 0
	s_waitcnt vmcnt(27)
	v_mfma_f32_16x16x32_bf16 v[2:5], v[96:99], v[100:103], v[2:5]
	v_mfma_f32_16x16x32_bf16 v[10:13], v[96:99], v[104:107], v[10:13]
	v_mfma_f32_16x16x32_bf16 v[14:17], v[96:99], v[108:111], v[14:17]
	v_mfma_f32_16x16x32_bf16 v[18:21], v[96:99], v[112:115], v[18:21]
	v_mfma_f32_16x16x32_bf16 v[22:25], v[96:99], v[116:119], v[22:25]
	v_mfma_f32_16x16x32_bf16 v[26:29], v[96:99], v[120:123], v[26:29]
	v_mfma_f32_16x16x32_bf16 v[30:33], v[96:99], v[124:127], v[30:33]
	v_mfma_f32_16x16x32_bf16 v[6:9], v[96:99], v[128:131], v[6:9]
	v_lshl_add_u64 v[96:97], v[34:35], 0, v[86:87]
	global_load_dwordx4 v[96:99], v[96:97], off
	global_load_dwordx4 v[100:103], v36, s[90:91]
	global_load_dwordx4 v[104:107], v36, s[90:91] offset:1024
	global_load_dwordx4 v[108:111], v36, s[90:91] offset:2048
	global_load_dwordx4 v[112:115], v36, s[90:91] offset:3072
	global_load_dwordx4 v[116:119], v36, s[92:93]
	global_load_dwordx4 v[120:123], v36, s[92:93] offset:1024
	global_load_dwordx4 v[124:127], v36, s[92:93] offset:2048
	global_load_dwordx4 v[128:131], v36, s[92:93] offset:3072
	s_add_u32 s90, s90, 0x2000
	s_addc_u32 s91, s91, 0
	s_add_u32 s92, s92, 0x2000
	s_addc_u32 s93, s93, 0
	s_waitcnt vmcnt(27)
	v_mfma_f32_16x16x32_bf16 v[2:5], v[132:135], v[136:139], v[2:5]
	v_mfma_f32_16x16x32_bf16 v[10:13], v[132:135], v[140:143], v[10:13]
	v_mfma_f32_16x16x32_bf16 v[14:17], v[132:135], v[144:147], v[14:17]
	v_mfma_f32_16x16x32_bf16 v[18:21], v[132:135], v[148:151], v[18:21]
	v_mfma_f32_16x16x32_bf16 v[22:25], v[132:135], v[152:155], v[22:25]
	v_mfma_f32_16x16x32_bf16 v[26:29], v[132:135], v[156:159], v[26:29]
	v_mfma_f32_16x16x32_bf16 v[30:33], v[132:135], v[160:163], v[30:33]
	v_mfma_f32_16x16x32_bf16 v[6:9], v[132:135], v[164:167], v[6:9]
	v_lshl_add_u64 v[132:133], v[34:35], 0, v[86:87]
	global_load_dwordx4 v[132:135], v[132:133], off offset:64
	global_load_dwordx4 v[136:139], v36, s[90:91]
	global_load_dwordx4 v[140:143], v36, s[90:91] offset:1024
	global_load_dwordx4 v[144:147], v36, s[90:91] offset:2048
	global_load_dwordx4 v[148:151], v36, s[90:91] offset:3072
	global_load_dwordx4 v[152:155], v36, s[92:93]
	global_load_dwordx4 v[156:159], v36, s[92:93] offset:1024
	global_load_dwordx4 v[160:163], v36, s[92:93] offset:2048
	global_load_dwordx4 v[164:167], v36, s[92:93] offset:3072
	s_add_u32 s90, s90, 0x2000
	s_addc_u32 s91, s91, 0
	s_add_u32 s92, s92, 0x2000
	s_addc_u32 s93, s93, 0
	s_waitcnt vmcnt(27)
; #define CP_LOAD(buf, s_) do { const int kabs_ = 512 * wid + 32 * (s_) + 8 * q; fa[buf] = *(const bf16x8*)(arow + (size_t)(kabs_ >> 7) * NPROJ + (kabs_ & 127)); \
;         _Pragma("unroll") for (int ct = 0; ct < 8; ++ct) fb[buf][ct] = *(const bf16x8*)(w1t + (size_t)(ct * 16 + r) * 4096 + kabs_); } while (0)
; DI void compress_item(const Params& P, int item, unsigned char* smem) {
;     ...
; #pragma unroll
;     for (int s = 0; s < 16; ++s) {
;         if (s + 1 < 16) CP_LOAD((s + 1) & 1, s + 1);
;         __builtin_amdgcn_sched_barrier(0);
; #pragma unroll
;         for (int ct = 0; ct < 8; ++ct) acc[ct] = __builtin_amdgcn_mfma_f32_16x16x32_bf16(fa[s & 1], fb[s & 1][ct], acc[ct], 0, 0, 0);
;         __builtin_amdgcn_sched_barrier(0);
;     }
;     ...
; #pragma unroll
;     for (int ct = 0; ct < 8; ++ct)
; #pragma unroll
;         for (int j = 0; j < 4; ++j) part[(wid * 16 + 4 * q + j) * 128 + ct * 16 + r] = acc[ct][j];
;     __syncthreads();
	v_mfma_f32_16x16x32_bf16 v[2:5], v[168:171], v[172:175], v[2:5]
	v_mfma_f32_16x16x32_bf16 v[10:13], v[168:171], v[176:179], v[10:13]
	v_mfma_f32_16x16x32_bf16 v[14:17], v[168:171], v[180:183], v[14:17]
	v_mfma_f32_16x16x32_bf16 v[18:21], v[168:171], v[184:187], v[18:21]
	v_mfma_f32_16x16x32_bf16 v[22:25], v[168:171], v[188:191], v[22:25]
	v_mfma_f32_16x16x32_bf16 v[26:29], v[168:171], v[192:195], v[26:29]
	v_mfma_f32_16x16x32_bf16 v[30:33], v[168:171], v[196:199], v[30:33]
	v_mfma_f32_16x16x32_bf16 v[6:9], v[168:171], v[200:203], v[6:9]
	v_lshl_add_u64 v[168:169], v[34:35], 0, v[86:87]
	global_load_dwordx4 v[168:171], v[168:169], off offset:128
	global_load_dwordx4 v[172:175], v36, s[90:91]
	global_load_dwordx4 v[176:179], v36, s[90:91] offset:1024
	global_load_dwordx4 v[180:183], v36, s[90:91] offset:2048
	global_load_dwordx4 v[184:187], v36, s[90:91] offset:3072
	global_load_dwordx4 v[188:191], v36, s[92:93]
	global_load_dwordx4 v[192:195], v36, s[92:93] offset:1024
	global_load_dwordx4 v[196:199], v36, s[92:93] offset:2048
	global_load_dwordx4 v[200:203], v36, s[92:93] offset:3072
	s_add_u32 s90, s90, 0x2000
	s_addc_u32 s91, s91, 0
	s_add_u32 s92, s92, 0x2000
	s_addc_u32 s93, s93, 0
	s_waitcnt vmcnt(27)
	v_mfma_f32_16x16x32_bf16 v[2:5], v[208:211], v[212:215], v[2:5]
	v_mfma_f32_16x16x32_bf16 v[10:13], v[208:211], v[216:219], v[10:13]
	v_mfma_f32_16x16x32_bf16 v[14:17], v[208:211], v[220:223], v[14:17]
	v_mfma_f32_16x16x32_bf16 v[18:21], v[208:211], v[224:227], v[18:21]
	v_mfma_f32_16x16x32_bf16 v[22:25], v[208:211], v[228:231], v[22:25]
	v_mfma_f32_16x16x32_bf16 v[26:29], v[208:211], v[232:235], v[26:29]
	v_mfma_f32_16x16x32_bf16 v[30:33], v[208:211], v[236:239], v[30:33]
	v_mfma_f32_16x16x32_bf16 v[6:9], v[208:211], v[240:243], v[6:9]
	v_lshl_add_u64 v[208:209], v[34:35], 0, v[86:87]
	global_load_dwordx4 v[208:211], v[208:209], off offset:192
	global_load_dwordx4 v[212:215], v36, s[90:91]
	global_load_dwordx4 v[216:219], v36, s[90:91] offset:1024
	global_load_dwordx4 v[220:223], v36, s[90:91] offset:2048
	global_load_dwordx4 v[224:227], v36, s[90:91] offset:3072
	global_load_dwordx4 v[228:231], v36, s[92:93]
	global_load_dwordx4 v[232:235], v36, s[92:93] offset:1024
	global_load_dwordx4 v[236:239], v36, s[92:93] offset:2048
	global_load_dwordx4 v[240:243], v36, s[92:93] offset:3072
	s_add_u32 s90, s90, 0x2000
	s_addc_u32 s91, s91, 0
	s_add_u32 s92, s92, 0x2000
	s_addc_u32 s93, s93, 0
	s_waitcnt vmcnt(27)
	v_mfma_f32_16x16x32_bf16 v[2:5], v[96:99], v[100:103], v[2:5]
	v_mfma_f32_16x16x32_bf16 v[10:13], v[96:99], v[104:107], v[10:13]
	v_mfma_f32_16x16x32_bf16 v[14:17], v[96:99], v[108:111], v[14:17]
	v_mfma_f32_16x16x32_bf16 v[18:21], v[96:99], v[112:115], v[18:21]
	v_mfma_f32_16x16x32_bf16 v[22:25], v[96:99], v[116:119], v[22:25]
	v_mfma_f32_16x16x32_bf16 v[26:29], v[96:99], v[120:123], v[26:29]
	v_mfma_f32_16x16x32_bf16 v[30:33], v[96:99], v[124:127], v[30:33]
	v_mfma_f32_16x16x32_bf16 v[6:9], v[96:99], v[128:131], v[6:9]
	s_waitcnt vmcnt(18)
	v_mfma_f32_16x16x32_bf16 v[2:5], v[132:135], v[136:139], v[2:5]
	v_mfma_f32_16x16x32_bf16 v[10:13], v[132:135], v[140:143], v[10:13]
	v_mfma_f32_16x16x32_bf16 v[14:17], v[132:135], v[144:147], v[14:17]
	v_mfma_f32_16x16x32_bf16 v[18:21], v[132:135], v[148:151], v[18:21]
	v_mfma_f32_16x16x32_bf16 v[22:25], v[132:135], v[152:155], v[22:25]
	v_mfma_f32_16x16x32_bf16 v[26:29], v[132:135], v[156:159], v[26:29]
	v_mfma_f32_16x16x32_bf16 v[30:33], v[132:135], v[160:163], v[30:33]
	v_mfma_f32_16x16x32_bf16 v[6:9], v[132:135], v[164:167], v[6:9]
	s_waitcnt vmcnt(9)
	v_mfma_f32_16x16x32_bf16 v[2:5], v[168:171], v[172:175], v[2:5]
	v_mfma_f32_16x16x32_bf16 v[10:13], v[168:171], v[176:179], v[10:13]
	v_mfma_f32_16x16x32_bf16 v[14:17], v[168:171], v[180:183], v[14:17]
	v_mfma_f32_16x16x32_bf16 v[18:21], v[168:171], v[184:187], v[18:21]
	v_mfma_f32_16x16x32_bf16 v[22:25], v[168:171], v[188:191], v[22:25]
	v_mfma_f32_16x16x32_bf16 v[26:29], v[168:171], v[192:195], v[26:29]
	v_mfma_f32_16x16x32_bf16 v[30:33], v[168:171], v[196:199], v[30:33]
	v_mfma_f32_16x16x32_bf16 v[6:9], v[168:171], v[200:203], v[6:9]
	s_waitcnt vmcnt(0)
	v_mfma_f32_16x16x32_bf16 v[2:5], v[208:211], v[212:215], v[2:5]
	v_mfma_f32_16x16x32_bf16 v[10:13], v[208:211], v[216:219], v[10:13]
	v_mfma_f32_16x16x32_bf16 v[14:17], v[208:211], v[220:223], v[14:17]
	v_mfma_f32_16x16x32_bf16 v[18:21], v[208:211], v[224:227], v[18:21]
	v_mfma_f32_16x16x32_bf16 v[22:25], v[208:211], v[228:231], v[22:25]
	v_mfma_f32_16x16x32_bf16 v[26:29], v[208:211], v[232:235], v[26:29]
	v_mfma_f32_16x16x32_bf16 v[30:33], v[208:211], v[236:239], v[30:33]
	v_mfma_f32_16x16x32_bf16 v[6:9], v[208:211], v[240:243], v[6:9]
	s_nop 7
	s_nop 2
	ds_write2_b32 v95, v2, v10 offset1:16
	ds_write2_b32 v95, v3, v11 offset0:128 offset1:144
	v_add_u32_e32 v2, 0x400, v95
	ds_write2_b32 v2, v4, v12 offset1:16
	ds_write2_b32 v2, v5, v13 offset0:128 offset1:144
	ds_write2_b32 v95, v14, v18 offset0:32 offset1:48
	ds_write2_b32 v95, v15, v19 offset0:160 offset1:176
	ds_write2_b32 v2, v16, v20 offset0:32 offset1:48
	ds_write2_b32 v2, v17, v21 offset0:160 offset1:176
	ds_write2_b32 v95, v22, v26 offset0:64 offset1:80
	ds_write2_b32 v95, v23, v27 offset0:192 offset1:208
	ds_write2_b32 v2, v24, v28 offset0:64 offset1:80
	ds_write2_b32 v2, v25, v29 offset0:192 offset1:208
	ds_write2_b32 v95, v30, v6 offset0:96 offset1:112
	ds_write2_b32 v95, v31, v7 offset0:224 offset1:240
	ds_write2_b32 v2, v32, v8 offset0:96 offset1:112
	ds_write2_b32 v2, v33, v9 offset0:224 offset1:240
	v_lshl_add_u64 v[2:3], s[4:5], 2, v[48:49]
	s_waitcnt lgkmcnt(0)
	s_barrier
; DI unsigned pk2(float a, float b) { f32x2_t v = {a, b}; return __builtin_bit_cast(unsigned, __builtin_convertvector(v, bf16x2_t)); }
; DI float gelu_tanh(float v) { const float z = 0.7978845608028654f * (v + 0.044715f * v * v * v); const float th = 1.0f - 2.0f * __builtin_amdgcn_rcpf(__builtin_amdgcn_exp2f(2.8853900817779268f * z) + 1.0f); return 0.5f * v * (1.0f + th); }
; DI void compress_item(const Params& P, int item, unsigned char* smem) {
;     ...
;     { const int row = tid >> 5, c4 = (tid & 31) * 4; f32x4 s = *(const f32x4*)(cb1 + c4);
; #pragma unroll
;       for (int w = 0; w < 8; ++w) s += *(const f32x4*)(part + (w * 16 + row) * 128 + c4);
;       u32x2 o; o.x = pk2(gelu_tanh(s[0]), gelu_tanh(s[1])); o.y = pk2(gelu_tanh(s[2]), gelu_tanh(s[3]));
;       *(u32x2*)(hid + row * 136 + c4) = o; }
;     __syncthreads();
;     { f32x4 a2 = {0.f, 0.f, 0.f, 0.f};
; #pragma unroll
;       for (int s = 0; s < 4; ++s) { const bf16x8 a = *(const bf16x8*)(hid + r * 136 + 32 * s + 8 * q);
;           const bf16x8 bb = *(const bf16x8*)(w2t + (size_t)(16 * wid + r) * 128 + 32 * s + 8 * q);
;           a2 = __builtin_amdgcn_mfma_f32_16x16x32_bf16(a, bb, a2, 0, 0, 0); }
;       bf16_t* kcb = (bf16_t*)(ws + WS_KCB); bf16_t* vcbt = (bf16_t*)(ws + WS_VCBT);
; #pragma unroll
;       for (int j = 0; j < 4; ++j) { const int gr = rt * 16 + 4 * q + j, bg2 = gr / 127, c2 = gr % 127, col = 16 * wid + r;
;           const bf16_t v = (bf16_t)(pk2(a2[j], 0.f) & 0xffffu);
;           if (which == 0) kcb[(size_t)(bg2 * 128 + c2) * 128 + col] = v; else vcbt[(size_t)(bg2 * 128 + col) * 128 + c2] = v; } }
	global_load_dwordx4 v[2:5], v[2:3], off
	ds_read_b128 v[6:9], v91
	ds_read_b128 v[10:13], v91 offset:8192
	ds_read_b128 v[14:17], v91 offset:16384
	ds_read_b128 v[18:21], v91 offset:24576
	ds_read_b128 v[22:25], v91 offset:32768
	ds_read_b128 v[26:29], v91 offset:40960
	ds_read_b128 v[30:33], v91 offset:49152
	ds_read_b128 v[34:37], v91 offset:57344
	v_lshl_add_u64 v[38:39], v[50:51], 0, s[14:15]
	s_mov_b64 s[4:5], -1
	s_and_b64 vcc, exec, s[46:47]
	s_waitcnt vmcnt(0) lgkmcnt(7)
	v_pk_add_f32 v[4:5], v[4:5], v[8:9]
	v_pk_add_f32 v[2:3], v[2:3], v[6:7]
	s_waitcnt lgkmcnt(6)
	v_pk_add_f32 v[4:5], v[4:5], v[12:13]
	v_pk_add_f32 v[2:3], v[2:3], v[10:11]
	s_waitcnt lgkmcnt(5)
	v_pk_add_f32 v[4:5], v[4:5], v[16:17]
	v_pk_add_f32 v[2:3], v[2:3], v[14:15]
	s_waitcnt lgkmcnt(4)
	v_pk_add_f32 v[4:5], v[4:5], v[20:21]
	v_pk_add_f32 v[2:3], v[2:3], v[18:19]
	s_waitcnt lgkmcnt(3)
	v_pk_add_f32 v[4:5], v[4:5], v[24:25]
	v_pk_add_f32 v[2:3], v[2:3], v[22:23]
	s_waitcnt lgkmcnt(2)
	v_pk_add_f32 v[4:5], v[4:5], v[28:29]
	v_pk_add_f32 v[2:3], v[2:3], v[26:27]
	s_waitcnt lgkmcnt(1)
	v_pk_add_f32 v[4:5], v[4:5], v[32:33]
	v_pk_add_f32 v[2:3], v[2:3], v[30:31]
	s_waitcnt lgkmcnt(0)
	v_pk_add_f32 v[4:5], v[4:5], v[36:37]
	v_pk_add_f32 v[2:3], v[2:3], v[34:35]
	v_mul_f32_e32 v8, 0x3d372713, v4
	v_mul_f32_e32 v6, 0x3d372713, v2
	v_mul_f32_e32 v7, 0x3d372713, v3
	v_mul_f32_e32 v9, 0x3d372713, v5
	v_mul_f32_e32 v6, v2, v6
	v_mul_f32_e32 v7, v3, v7
	v_mul_f32_e32 v8, v4, v8
	v_mul_f32_e32 v9, v5, v9
	v_fma_f32 v6, v2, v6, v2
	v_fma_f32 v7, v3, v7, v3
	v_fma_f32 v8, v4, v8, v4
	v_fma_f32 v9, v5, v9, v5
	v_mul_f32_e32 v6, 0x3f4c422a, v6
	v_mul_f32_e32 v7, 0x3f4c422a, v7
	v_mul_f32_e32 v8, 0x3f4c422a, v8
	v_mul_f32_e32 v9, 0x3f4c422a, v9
	v_mul_f32_e32 v6, 0x4038aa3b, v6
	v_mul_f32_e32 v7, 0x4038aa3b, v7
	v_mul_f32_e32 v8, 0x4038aa3b, v8
	v_mul_f32_e32 v9, 0x4038aa3b, v9
	v_exp_f32_e32 v6, v6
	v_exp_f32_e32 v7, v7
	v_exp_f32_e32 v8, v8
	v_exp_f32_e32 v9, v9
	v_add_f32_e32 v6, 1.0, v6
	v_add_f32_e32 v7, 1.0, v7
	v_add_f32_e32 v8, 1.0, v8
	v_add_f32_e32 v9, 1.0, v9
	v_rcp_f32_e32 v6, v6
	v_rcp_f32_e32 v7, v7
	v_rcp_f32_e32 v8, v8
	v_rcp_f32_e32 v9, v9
	v_pk_mul_f32 v[2:3], v[2:3], 0.5 op_sel_hi:[1,0]
	v_pk_fma_f32 v[6:7], v[6:7], 2.0, 1.0 op_sel_hi:[1,0,0] neg_lo:[1,0,0] neg_hi:[1,0,0]
	v_pk_mul_f32 v[4:5], v[4:5], 0.5 op_sel_hi:[1,0]
	v_pk_fma_f32 v[8:9], v[8:9], 2.0, 1.0 op_sel_hi:[1,0,0] neg_lo:[1,0,0] neg_hi:[1,0,0]
	v_pk_add_f32 v[6:7], v[6:7], 1.0 op_sel_hi:[1,0]
	v_pk_add_f32 v[8:9], v[8:9], 1.0 op_sel_hi:[1,0]
	v_pk_mul_f32 v[2:3], v[2:3], v[6:7]
	v_pk_mul_f32 v[4:5], v[4:5], v[8:9]
	v_cvt_pk_bf16_f32 v2, v2, v3
	v_cvt_pk_bf16_f32 v3, v4, v5
	ds_write_b64 v92, v[2:3]
	s_waitcnt lgkmcnt(0)
	s_barrier
	global_load_dwordx4 v[2:5], v[38:39], off
	global_load_dwordx4 v[8:11], v[38:39], off offset:64
	global_load_dwordx4 v[12:15], v[38:39], off offset:128
	global_load_dwordx4 v[16:19], v[38:39], off offset:192
	ds_read_b128 v[20:23], v93
	ds_read_b128 v[24:27], v93 offset:64
	ds_read_b128 v[28:31], v93 offset:128
	v_add_u32_e32 v7, s33, v90
	v_add_u32_e32 v6, s73, v7
	s_waitcnt vmcnt(3) lgkmcnt(2)
	v_mfma_f32_16x16x32_bf16 v[2:5], v[20:23], v[2:5], 0
	ds_read_b128 v[20:23], v93 offset:192
	s_waitcnt vmcnt(2) lgkmcnt(2)
	v_mfma_f32_16x16x32_bf16 v[2:5], v[24:27], v[8:11], v[2:5]
	v_mul_hi_i32 v8, v6, s59
	v_add_u32_e32 v8, v8, v6
	v_lshrrev_b32_e32 v9, 31, v8
	s_waitcnt vmcnt(1) lgkmcnt(1)
	v_mfma_f32_16x16x32_bf16 v[2:5], v[28:31], v[12:15], v[2:5]
	v_ashrrev_i32_e32 v8, 6, v8
	v_add_u32_e32 v8, v8, v9
	s_waitcnt vmcnt(0) lgkmcnt(0)
	v_mfma_f32_16x16x32_bf16 v[2:5], v[20:23], v[16:19], v[2:5]
	s_nop 7
	v_cvt_pk_bf16_f32 v2, v2, s0
	s_cbranch_vccz .LBB0_640
	v_mul_lo_u32 v9, v8, s68
	v_lshl_add_u32 v12, v8, 7, v94
	v_subrev_u32_e32 v9, s72, v9
	v_ashrrev_i32_e32 v13, 31, v12
	v_add_u32_e32 v10, v7, v9
	v_lshlrev_b64 v[12:13], 8, v[12:13]
	v_ashrrev_i32_e32 v11, 31, v10
	v_lshl_add_u64 v[12:13], s[10:11], 0, v[12:13]
	v_lshl_add_u64 v[10:11], v[10:11], 1, v[12:13]
	global_store_short v[10:11], v2, off
	s_mov_b64 s[4:5], 0
